# diff attention producer QK: 2-step-deep K-fragment LDS prefetch (3 rotating register sets), P(j-1) read after QK; on top of v90
# baseline (speedup 1.0000x reference)
; #define SBAR() __builtin_amdgcn_sched_barrier(0)
; template <int NQK, int NREG>
; __device__ __forceinline__ void qkt(f32x16& p0, f32x16& p1, const char* Ks, const char* KRs, const bf16x8* qr, const char* qrl, int r32, int hi) {
;   p0 = f32x16{}; p1 = f32x16{};
; #pragma unroll
;   for (int d0 = 0; d0 < 8; ++d0) { const int cb = (d0 * 16 + hi * 8) * 2;
;     bf16x8 b0 = *reinterpret_cast<const bf16x8*>(Ks + KSWZ(r32, cb));
;     bf16x8 b1 = *reinterpret_cast<const bf16x8*>(Ks + KSWZ(32 + r32, cb));
;     bf16x8 qq; if (d0 < NREG) qq = qr[d0 < NREG ? d0 : 0]; else qq = *reinterpret_cast<const bf16x8*>(qrl + KRSWZ(r32, (d0 - 4) * 2 + hi));
;     p0 = __builtin_amdgcn_mfma_f32_32x32x16_bf16(b0, qq, p0, 0, 0, 0);
;     p1 = __builtin_amdgcn_mfma_f32_32x32x16_bf16(b1, qq, p1, 0, 0, 0); }
; __device__ __forceinline__ void attn_core_pair(f32x16 (&o)[4], const bf16_t* __restrict__ Qb, const bf16_t* __restrict__ Kh, const bf16_t* __restrict__ Vh, const int seq, const float C, const float thr_raw, char* lds) {
;     ...
;       float m_reg = (j == 0) ? -1e30f : m_l[r32], l_reg = (j == 0) ? 0.f : l_l[r32], mn, al;
;       SBAR(); qkt<8, 8>(p0, p1, K_lds + kb * SHM_K, nullptr, qr, nullptr, r32, hi);
.LBB0_381:
	s_and_b32 s57, s40, 1
	s_xor_b32 s30, s57, 1
	s_mov_b32 s99, s30
	v_cmp_ne_u32_e32 vcc, s30, v157
	s_and_saveexec_b64 s[30:31], vcc
	s_cbranch_execz .Ldiff_cons
	ds_read_b32 v163, v203
	ds_read_b32 v169, v201
	v_add_u32_e32 v171, v205, v155
	ds_read_b128 v[228:231], v171
	ds_read_b128 v[232:235], v171 offset:8192
	v_add_u32_e32 v171, v206, v155
	ds_read_b128 v[240:243], v171
	ds_read_b128 v[244:247], v171 offset:8192
	v_add_u32_e32 v171, v207, v155
	ds_read_b128 v[248:251], v171
	ds_read_b128 v[252:255], v171 offset:8192
	s_waitcnt lgkmcnt(4)
	v_mfma_f32_32x32x16_bf16 v[80:95], v[228:231], v[124:127], 0
	v_mfma_f32_32x32x16_bf16 v[64:79], v[232:235], v[124:127], 0
	v_add_u32_e32 v171, v208, v155
	ds_read_b128 v[228:231], v171
	ds_read_b128 v[232:235], v171 offset:8192
	s_waitcnt lgkmcnt(4)
	v_mfma_f32_32x32x16_bf16 v[80:95], v[240:243], v[120:123], v[80:95]
	v_mfma_f32_32x32x16_bf16 v[64:79], v[244:247], v[120:123], v[64:79]
	v_add_u32_e32 v171, v209, v155
	ds_read_b128 v[240:243], v171
	ds_read_b128 v[244:247], v171 offset:8192
	s_waitcnt lgkmcnt(4)
	v_mfma_f32_32x32x16_bf16 v[80:95], v[248:251], v[116:119], v[80:95]
	v_mfma_f32_32x32x16_bf16 v[64:79], v[252:255], v[116:119], v[64:79]
	v_add_u32_e32 v171, v210, v155
	ds_read_b128 v[248:251], v171
	ds_read_b128 v[252:255], v171 offset:8192
	s_waitcnt lgkmcnt(4)
	v_mfma_f32_32x32x16_bf16 v[80:95], v[228:231], v[112:115], v[80:95]
	v_mfma_f32_32x32x16_bf16 v[64:79], v[232:235], v[112:115], v[64:79]
	v_add_u32_e32 v171, v211, v155
	ds_read_b128 v[228:231], v171
	ds_read_b128 v[232:235], v171 offset:8192
	s_waitcnt lgkmcnt(4)
	v_mfma_f32_32x32x16_bf16 v[80:95], v[240:243], v[108:111], v[80:95]
	v_mfma_f32_32x32x16_bf16 v[64:79], v[244:247], v[108:111], v[64:79]
	v_add_u32_e32 v171, v212, v155
	ds_read_b128 v[240:243], v171
	ds_read_b128 v[244:247], v171 offset:8192
	s_waitcnt lgkmcnt(4)
	v_mfma_f32_32x32x16_bf16 v[80:95], v[248:251], v[104:107], v[80:95]
	v_mfma_f32_32x32x16_bf16 v[64:79], v[252:255], v[104:107], v[64:79]
	s_waitcnt lgkmcnt(2)
	v_mfma_f32_32x32x16_bf16 v[80:95], v[228:231], v[100:103], v[80:95]
	v_mfma_f32_32x32x16_bf16 v[64:79], v[232:235], v[100:103], v[64:79]
	s_waitcnt lgkmcnt(0)
; __device__ __forceinline__ void partialSM(f32x16& p0, f32x16& p1, float& m_reg, float& mn, float& alpha, const float C, const float thr_raw) {
;   float pmax = p0[0];
; #pragma unroll
;   for (int r = 1; r < 16; ++r) pmax = fmaxf(pmax, p0[r]);
; #pragma unroll
;   for (int r = 0; r < 16; ++r) pmax = fmaxf(pmax, p1[r]);
;   { auto rr = __builtin_amdgcn_permlane32_swap(__float_as_uint(pmax), __float_as_uint(pmax), false, false);
;     pmax = fmaxf(__uint_as_float(rr[0]), __uint_as_float(rr[1])); }
;   if (__builtin_expect(__all(pmax - m_reg <= thr_raw), 1)) { mn = m_reg; alpha = 1.f; }
;   else { mn = fmaxf(m_reg, pmax); alpha = __builtin_amdgcn_exp2f((m_reg - mn) * C); m_reg = mn; }
;   const float mnC = -mn * C;
; #pragma unroll
;   for (int r = 0; r < 16; ++r) p0[r] = fmaf(p0[r], C, mnC);
; #pragma unroll
;   for (int r = 0; r < 16; ++r) p1[r] = fmaf(p1[r], C, mnC);
; #pragma unroll
;   for (int r = 0; r < 16; ++r) p0[r] = __builtin_amdgcn_exp2f(p0[r]);
; }
; __device__ __forceinline__ void finishSM(f32x16& p0, f32x16& p1, float alpha, float& l_reg, bf16x8& pa0, bf16x8& pa1, bf16x8& pa2, bf16x8& pa3) {
; #pragma unroll
;   for (int r = 0; r < 16; ++r) p1[r] = __builtin_amdgcn_exp2f(p1[r]);
;   float ps = 0;
; #pragma unroll
;   for (int r = 0; r < 16; ++r) ps += p0[r];
; #pragma unroll
;   for (int r = 0; r < 16; ++r) ps += p1[r];
;   { auto rr = __builtin_amdgcn_permlane32_swap(__float_as_uint(ps), __float_as_uint(ps), false, false);
;     ps = __uint_as_float(rr[0]) + __uint_as_float(rr[1]); }
;   l_reg = l_reg * alpha + ps;
;     ...
;   PK4(p0, 0, pa0); PK4(p0, 8, pa1); PK4(p1, 0, pa2); PK4(p1, 8, pa3);
;     ...
; }
; template <int NQK, int NREG>
; __device__ __forceinline__ void qkt(f32x16& p0, f32x16& p1, const char* Ks, const char* KRs, const bf16x8* qr, const char* qrl, int r32, int hi) {
;   p0 = f32x16{}; p1 = f32x16{};
; #pragma unroll
;   for (int d0 = 0; d0 < 8; ++d0) { const int cb = (d0 * 16 + hi * 8) * 2;
;     bf16x8 b0 = *reinterpret_cast<const bf16x8*>(Ks + KSWZ(r32, cb));
;     bf16x8 b1 = *reinterpret_cast<const bf16x8*>(Ks + KSWZ(32 + r32, cb));
;     bf16x8 qq; if (d0 < NREG) qq = qr[d0 < NREG ? d0 : 0]; else qq = *reinterpret_cast<const bf16x8*>(qrl + KRSWZ(r32, (d0 - 4) * 2 + hi));
;     p0 = __builtin_amdgcn_mfma_f32_32x32x16_bf16(b0, qq, p0, 0, 0, 0);
;     p1 = __builtin_amdgcn_mfma_f32_32x32x16_bf16(b1, qq, p1, 0, 0, 0); }
	v_mfma_f32_32x32x16_bf16 v[80:95], v[240:243], v[96:99], v[80:95]
	v_mfma_f32_32x32x16_bf16 v[64:79], v[244:247], v[96:99], v[64:79]
	ds_read_b128 v[240:243], v225
	ds_read_b128 v[244:247], v225 offset:1024
	ds_read_b128 v[248:251], v225 offset:2048
	ds_read_b128 v[252:255], v225 offset:3072
	s_nop 10
	v_max_f32_e32 v171, v81, v81
	v_max_f32_e32 v173, v80, v80
	v_max_f32_e32 v171, v173, v171
	v_max3_f32 v171, v171, v82, v83
	v_max3_f32 v171, v171, v84, v85
	v_max3_f32 v171, v171, v86, v87
	v_max3_f32 v171, v171, v88, v89
	v_max3_f32 v171, v171, v90, v91
	v_max3_f32 v171, v171, v92, v93
	v_max3_f32 v171, v171, v94, v95
	v_max3_f32 v171, v171, v64, v65
	v_max3_f32 v171, v171, v66, v67
	v_max3_f32 v171, v171, v68, v69
	v_max3_f32 v171, v171, v70, v71
	v_max3_f32 v171, v171, v72, v73
	v_max3_f32 v171, v171, v74, v75
	v_max3_f32 v171, v171, v76, v77
	v_max3_f32 v171, v171, v78, v79
	v_mov_b32_e32 v173, v171
	s_nop 1
	v_permlane32_swap_b32_e32 v171, v173
	v_max_f32_e32 v173, v173, v173
	v_max_f32_e32 v171, v171, v171
	v_max_f32_e32 v171, v171, v173
	v_sub_f32_e32 v173, v171, v169
	v_cmp_ge_f32_e32 vcc, s47, v173
	v_max_f32_e32 v173, v169, v169
	v_max_f32_e32 v171, v173, v171
	v_sub_f32_e32 v173, v169, v171
	v_mul_f32_e32 v173, 0x3e0293ee, v173
	v_exp_f32_e32 v173, v173
	s_cmp_eq_u64 vcc, exec
	s_cselect_b64 vcc, -1, 0
	v_cndmask_b32_e32 v171, v171, v169, vcc
	v_cndmask_b32_e64 v169, v173, 1.0, vcc
	v_mul_f32_e32 v173, 0xbe0293ee, v171
	v_fmamk_f32 v80, v80, 0x3e0293ee, v173
	v_fmamk_f32 v81, v81, 0x3e0293ee, v173
	v_fmamk_f32 v82, v82, 0x3e0293ee, v173
	v_fmamk_f32 v83, v83, 0x3e0293ee, v173
	v_fmamk_f32 v84, v84, 0x3e0293ee, v173
	v_fmamk_f32 v85, v85, 0x3e0293ee, v173
	v_fmamk_f32 v86, v86, 0x3e0293ee, v173
	v_fmamk_f32 v87, v87, 0x3e0293ee, v173
	v_fmamk_f32 v88, v88, 0x3e0293ee, v173
	v_fmamk_f32 v89, v89, 0x3e0293ee, v173
	v_fmamk_f32 v90, v90, 0x3e0293ee, v173
	v_fmamk_f32 v91, v91, 0x3e0293ee, v173
	v_fmamk_f32 v92, v92, 0x3e0293ee, v173
	v_fmamk_f32 v93, v93, 0x3e0293ee, v173
	v_fmamk_f32 v94, v94, 0x3e0293ee, v173
	v_fmamk_f32 v95, v95, 0x3e0293ee, v173
	v_fmamk_f32 v64, v64, 0x3e0293ee, v173
	v_fmamk_f32 v65, v65, 0x3e0293ee, v173
	v_fmamk_f32 v66, v66, 0x3e0293ee, v173
	v_fmamk_f32 v67, v67, 0x3e0293ee, v173
	v_fmamk_f32 v68, v68, 0x3e0293ee, v173
	v_fmamk_f32 v69, v69, 0x3e0293ee, v173
	v_fmamk_f32 v70, v70, 0x3e0293ee, v173
	v_fmamk_f32 v71, v71, 0x3e0293ee, v173
	v_fmamk_f32 v72, v72, 0x3e0293ee, v173
	v_fmamk_f32 v73, v73, 0x3e0293ee, v173
	v_fmamk_f32 v74, v74, 0x3e0293ee, v173
	v_fmamk_f32 v75, v75, 0x3e0293ee, v173
	v_fmamk_f32 v76, v76, 0x3e0293ee, v173
	v_fmamk_f32 v77, v77, 0x3e0293ee, v173
	v_fmamk_f32 v78, v78, 0x3e0293ee, v173
	v_fmac_f32_e32 v173, 0x3e0293ee, v79
	v_exp_f32_e32 v79, v80
	v_exp_f32_e32 v175, v81
	v_exp_f32_e32 v82, v82
	v_exp_f32_e32 v83, v83
	v_exp_f32_e32 v84, v84
	v_exp_f32_e32 v183, v64
	v_add_f32_e32 v64, 0, v79
	v_exp_f32_e32 v85, v85
	v_add_f32_e32 v64, v175, v64
	v_exp_f32_e32 v86, v86
	v_add_f32_e32 v64, v82, v64
	v_exp_f32_e32 v87, v87
	v_add_f32_e32 v64, v83, v64
	v_exp_f32_e32 v88, v88
	v_add_f32_e32 v64, v84, v64
	v_exp_f32_e32 v89, v89
	v_add_f32_e32 v64, v85, v64
	v_exp_f32_e32 v90, v90
	v_add_f32_e32 v64, v86, v64
	v_exp_f32_e32 v91, v91
	v_add_f32_e32 v64, v87, v64
	v_exp_f32_e32 v92, v92
	v_add_f32_e32 v64, v88, v64
	v_exp_f32_e32 v93, v93
	v_add_f32_e32 v64, v89, v64
	v_exp_f32_e32 v94, v94
	v_add_f32_e32 v64, v90, v64
	v_exp_f32_e32 v95, v95
	v_add_f32_e32 v64, v91, v64
	v_add_f32_e32 v64, v92, v64
	v_exp_f32_e32 v185, v65
	v_add_f32_e32 v64, v93, v64
	v_exp_f32_e32 v227, v66
	v_add_f32_e32 v64, v94, v64
	v_exp_f32_e32 v228, v67
	v_add_f32_e32 v64, v95, v64
	v_exp_f32_e32 v229, v68
	v_add_f32_e32 v64, v183, v64
	v_exp_f32_e32 v230, v69
	v_add_f32_e32 v64, v185, v64
	v_exp_f32_e32 v231, v70
	v_add_f32_e32 v64, v227, v64
	v_exp_f32_e32 v232, v71
	v_add_f32_e32 v64, v228, v64
	v_exp_f32_e32 v72, v72
	v_add_f32_e32 v64, v229, v64
	v_exp_f32_e32 v73, v73
	v_add_f32_e32 v64, v230, v64
	v_exp_f32_e32 v74, v74
	v_add_f32_e32 v64, v231, v64
	v_exp_f32_e32 v75, v75
	v_add_f32_e32 v64, v232, v64
	v_exp_f32_e32 v233, v76
	v_add_f32_e32 v64, v72, v64
	v_exp_f32_e32 v234, v77
	v_add_f32_e32 v64, v73, v64
	v_exp_f32_e32 v235, v78
	v_add_f32_e32 v64, v74, v64
	v_exp_f32_e32 v173, v173
	v_add_f32_e32 v64, v75, v64
	v_add_f32_e32 v64, v233, v64
	v_add_f32_e32 v64, v234, v64
	v_add_f32_e32 v64, v235, v64
	v_add_f32_e32 v80, v173, v64
	v_mov_b32_e32 v81, v80
	v_cvt_pk_bf16_f32 v64, v79, v175
	v_cvt_pk_bf16_f32 v65, v82, v83
	v_cvt_pk_bf16_f32 v66, v84, v85
	v_cvt_pk_bf16_f32 v67, v86, v87
	v_cvt_pk_bf16_f32 v68, v88, v89
	v_cvt_pk_bf16_f32 v69, v90, v91
	v_cvt_pk_bf16_f32 v70, v92, v93
	v_cvt_pk_bf16_f32 v71, v94, v95
	v_cvt_pk_bf16_f32 v76, v183, v185
	v_cvt_pk_bf16_f32 v77, v227, v228
	v_cvt_pk_bf16_f32 v78, v229, v230
	v_cvt_pk_bf16_f32 v79, v231, v232
	v_cvt_pk_bf16_f32 v72, v72, v73
	v_cvt_pk_bf16_f32 v73, v74, v75
	v_cvt_pk_bf16_f32 v74, v233, v234
	v_cvt_pk_bf16_f32 v75, v235, v173
	s_nop 1
	v_permlane32_swap_b32_e32 v80, v81
	v_permlane32_swap_b32_e32 v64, v66
	v_permlane32_swap_b32_e32 v65, v67
	v_permlane32_swap_b32_e32 v68, v70
	v_permlane32_swap_b32_e32 v69, v71
	v_permlane32_swap_b32_e32 v76, v78
	v_permlane32_swap_b32_e32 v77, v79
	v_permlane32_swap_b32_e32 v72, v74
	v_permlane32_swap_b32_e32 v73, v75
	v_lshl_add_u32 v82, s99, 4, v200
	ds_read_b32 v82, v82
	v_cmp_gt_f32_e32 vcc, 1.0, v169
	ds_write_b128 v225, v[64:67]
	ds_write_b128 v225, v[68:71] offset:1024
	ds_write_b128 v225, v[76:79] offset:2048
	ds_write_b128 v225, v[72:75] offset:3072
	s_and_saveexec_b64 s[38:39], s[2:3]
	s_cbranch_execz .LBB0_388
	v_add_f32_e32 v80, v80, v81
	v_fmac_f32_e32 v80, v163, v169
	ds_write_b32 v201, v171
	ds_write_b32 v203, v80
	v_add_u32_e32 v80, v201, v213
	ds_write_b32 v80, v169 offset:1024
